# stack2 + scan2 step loop: counted vmcnt (22/19/3 by wave) instead of vmcnt(0) drains so the 4-step register prefetch really hides global latency
# speedup vs baseline: 1.0021x; 1.0021x over previous
; __device__ __forceinline__ void phase_scan2(Frame& F, int l) {
;     ...
;         for (int c = 0; c < nch; c += 4) {
;             S2_STEP(c, bm, bn); if (c + 1 >= nch) break;
;             S2_STEP(c + 1, cm, cn); if (c + 2 >= nch) break;
.LBB0_660:
	s_add_i32 s11, s36, -7
	s_cmp_lt_u32 s11, s21
	s_cselect_b64 s[28:29], -1, 0
	s_cmp_ge_u32 s11, s21
	s_cbranch_scc0 .LBB0_688
	s_add_i32 s11, s36, -3
	s_waitcnt vmcnt(0)
	s_cmp_ge_u32 s11, s21
	s_cbranch_scc0 .LBB0_691

; __device__ __forceinline__ void phase_scan2(Frame& F, int l) {
;     ...
;         for (int c = 0; c < nch; c += 4) {
;             S2_STEP(c, bm, bn); if (c + 1 >= nch) break;
;             S2_STEP(c + 1, cm, cn); if (c + 2 >= nch) break;
.LBB0_666:
	s_waitcnt lgkmcnt(0)
	s_barrier
	s_andn2_b64 vcc, exec, s[28:29]
	s_mov_b64 s[28:29], -1
	s_cbranch_vccnz .LBB0_659
	s_add_i32 s11, s36, -6
	s_cmp_lt_u32 s11, s21
	s_cselect_b64 s[28:29], -1, 0
	s_cmp_ge_u32 s11, s21
	s_cbranch_scc0 .LBB0_694
	s_add_i32 s11, s36, -2
	s_waitcnt vmcnt(0)
	s_cmp_ge_u32 s11, s21
	s_cbranch_scc0 .LBB0_697

; __device__ __forceinline__ void phase_scan2(Frame& F, int l) {
;     ...
;         for (int c = 0; c < nch; c += 4) {
;             S2_STEP(c, bm, bn); if (c + 1 >= nch) break;
;             S2_STEP(c + 1, cm, cn); if (c + 2 >= nch) break;
;             S2_STEP(c + 2, dm, dn); if (c + 3 >= nch) break;
.LBB0_673:
	s_waitcnt lgkmcnt(0)
	s_barrier
	s_andn2_b64 vcc, exec, s[28:29]
	s_mov_b64 s[28:29], -1
	s_cbranch_vccnz .LBB0_659
	s_add_i32 s11, s36, -5
	s_cmp_lt_u32 s11, s21
	s_cselect_b64 s[28:29], -1, 0
	s_cmp_ge_u32 s11, s21
	s_cbranch_scc0 .LBB0_700
	s_add_i32 s11, s36, -1
	s_waitcnt vmcnt(0)
	s_cmp_ge_u32 s11, s21
	s_cbranch_scc0 .LBB0_703

; __device__ __forceinline__ void phase_scan2(Frame& F, int l) {
;     ...
;         for (int c = 0; c < nch; c += 4) {
;             S2_STEP(c, bm, bn); if (c + 1 >= nch) break;
;             S2_STEP(c + 1, cm, cn); if (c + 2 >= nch) break;
;             S2_STEP(c + 2, dm, dn); if (c + 3 >= nch) break;
;             S2_STEP(c + 3, am, an);
.LBB0_680:
	s_waitcnt lgkmcnt(0)
	s_barrier
	s_andn2_b64 vcc, exec, s[28:29]
	s_mov_b64 s[28:29], -1
	s_cbranch_vccnz .LBB0_659
	s_add_i32 s30, s36, -4
	s_cmp_ge_u32 s30, s21
	s_cbranch_scc0 .LBB0_706
	s_waitcnt vmcnt(0)
	s_cmp_ge_u32 s36, s21
	s_cbranch_scc0 .LBB0_709

.LBB0_688:
	s_add_i32 s11, s36, -3
	s_cmp_lt_u32 s11, s21
	s_cbranch_scc0 .Ls2w0_drain
	s_cmp_lt_u32 s36, 12
	s_cbranch_scc1 .Ls2w0_drain
	s_cmp_lt_u32 s47, 4
	s_cbranch_scc0 .Ls2w0_v3
	s_cmp_lt_u32 s47, 2
	s_cbranch_scc0 .Ls2w0_v19
	s_waitcnt vmcnt(22)
	s_branch .Ls2w0_go
.Ls2w0_v19:
	s_waitcnt vmcnt(19)
	s_branch .Ls2w0_go
.Ls2w0_v3:
	s_waitcnt vmcnt(3)
	s_branch .Ls2w0_go

.Ls2w0_go:
	ds_write_b128 v64, v[16:19] offset:9216
	s_and_saveexec_b64 s[30:31], s[6:7]
	s_cbranch_execz .LBB0_690
	v_lshlrev_b32_e32 v74, 16, v4
	v_and_b32_e32 v75, 0xffff0000, v4
	v_lshlrev_b32_e32 v76, 16, v5
	v_and_b32_e32 v77, 0xffff0000, v5
	ds_write_b128 v65, v[74:77] offset:22528
	v_lshlrev_b32_e32 v74, 16, v6
	v_and_b32_e32 v75, 0xffff0000, v6
	v_lshlrev_b32_e32 v76, 16, v7
	v_and_b32_e32 v77, 0xffff0000, v7
	ds_write_b128 v65, v[74:77] offset:22544

.LBB0_691:
	s_add_i32 s30, s10, 0xffffff40
	s_ashr_i32 s31, s30, 31
	v_lshl_add_u64 v[16:17], s[30:31], 0, v[42:43]
	v_lshlrev_b64 v[16:17], 12, v[16:17]
	v_lshl_add_u64 v[16:17], v[56:57], 0, v[16:17]
	global_load_dwordx4 v[16:19], v[16:17], off
	s_and_saveexec_b64 s[34:35], s[6:7]
	s_cbranch_execz .LBB0_693
	v_lshl_add_u64 v[4:5], v[58:59], 0, s[30:31]
	v_lshlrev_b64 v[4:5], 11, v[4:5]
	v_lshl_add_u64 v[4:5], v[60:61], 0, v[4:5]
	global_load_dwordx4 v[4:7], v[4:5], off

.LBB0_694:
	s_add_i32 s11, s36, -2
	s_cmp_lt_u32 s11, s21
	s_cbranch_scc0 .Ls2w1_drain
	s_cmp_lt_u32 s36, 12
	s_cbranch_scc1 .Ls2w1_drain
	s_cmp_lt_u32 s47, 4
	s_cbranch_scc0 .Ls2w1_v3
	s_cmp_lt_u32 s47, 2
	s_cbranch_scc0 .Ls2w1_v19
	s_waitcnt vmcnt(22)
	s_branch .Ls2w1_go

.Ls2w1_go:
	ds_write_b128 v41, v[24:27]
	s_and_saveexec_b64 s[30:31], s[6:7]
	s_cbranch_execz .LBB0_696
	v_lshlrev_b32_e32 v74, 16, v8
	v_and_b32_e32 v75, 0xffff0000, v8
	v_lshlrev_b32_e32 v76, 16, v9
	v_and_b32_e32 v77, 0xffff0000, v9
	ds_write_b128 v65, v[74:77] offset:18432
	v_lshlrev_b32_e32 v74, 16, v10
	v_and_b32_e32 v75, 0xffff0000, v10
	v_lshlrev_b32_e32 v76, 16, v11
	v_and_b32_e32 v77, 0xffff0000, v11
	ds_write_b128 v65, v[74:77] offset:18448

.LBB0_697:
	s_add_i32 s30, s10, 0xffffff80
	s_ashr_i32 s31, s30, 31
	v_lshl_add_u64 v[24:25], s[30:31], 0, v[42:43]
	v_lshlrev_b64 v[24:25], 12, v[24:25]
	v_lshl_add_u64 v[24:25], v[56:57], 0, v[24:25]
	global_load_dwordx4 v[24:27], v[24:25], off
	s_and_saveexec_b64 s[34:35], s[6:7]
	s_cbranch_execz .LBB0_699
	v_lshl_add_u64 v[8:9], v[58:59], 0, s[30:31]
	v_lshlrev_b64 v[8:9], 11, v[8:9]
	v_lshl_add_u64 v[8:9], v[60:61], 0, v[8:9]
	global_load_dwordx4 v[8:11], v[8:9], off

.LBB0_700:
	s_add_i32 s11, s36, -1
	s_cmp_lt_u32 s11, s21
	s_cbranch_scc0 .Ls2w2_drain
	s_cmp_lt_u32 s36, 12
	s_cbranch_scc1 .Ls2w2_drain
	s_cmp_lt_u32 s47, 4
	s_cbranch_scc0 .Ls2w2_v3
	s_cmp_lt_u32 s47, 2
	s_cbranch_scc0 .Ls2w2_v19
	s_waitcnt vmcnt(22)
	s_branch .Ls2w2_go

.Ls2w2_go:
	ds_write_b128 v64, v[28:31] offset:9216
	s_and_saveexec_b64 s[30:31], s[6:7]
	s_cbranch_execz .LBB0_702
	v_lshlrev_b32_e32 v74, 16, v12
	v_and_b32_e32 v75, 0xffff0000, v12
	v_lshlrev_b32_e32 v76, 16, v13
	v_and_b32_e32 v77, 0xffff0000, v13
	ds_write_b128 v65, v[74:77] offset:22528
	v_lshlrev_b32_e32 v74, 16, v14
	v_and_b32_e32 v75, 0xffff0000, v14
	v_lshlrev_b32_e32 v76, 16, v15
	v_and_b32_e32 v77, 0xffff0000, v15
	ds_write_b128 v65, v[74:77] offset:22544

.LBB0_703:
	s_sub_i32 s30, s10, 64
	s_ashr_i32 s31, s30, 31
	v_lshl_add_u64 v[28:29], s[30:31], 0, v[42:43]
	v_lshlrev_b64 v[28:29], 12, v[28:29]
	v_lshl_add_u64 v[28:29], v[56:57], 0, v[28:29]
	global_load_dwordx4 v[28:31], v[28:29], off
	s_and_saveexec_b64 s[34:35], s[6:7]
	s_cbranch_execz .LBB0_705
	v_lshl_add_u64 v[12:13], v[58:59], 0, s[30:31]
	v_lshlrev_b64 v[12:13], 11, v[12:13]
	v_lshl_add_u64 v[12:13], v[60:61], 0, v[12:13]
	global_load_dwordx4 v[12:15], v[12:13], off

.LBB0_706:
	s_mov_b32 s11, s36
	s_cmp_lt_u32 s11, s21
	s_cbranch_scc0 .Ls2w3_drain
	s_cmp_lt_u32 s36, 12
	s_cbranch_scc1 .Ls2w3_drain
	s_cmp_lt_u32 s47, 4
	s_cbranch_scc0 .Ls2w3_v3
	s_cmp_lt_u32 s47, 2
	s_cbranch_scc0 .Ls2w3_v19
	s_waitcnt vmcnt(22)
	s_branch .Ls2w3_go

.Ls2w3_go:
	ds_write_b128 v41, v[32:35]
	s_and_saveexec_b64 s[28:29], s[6:7]
	s_cbranch_execz .LBB0_708
	v_lshlrev_b32_e32 v74, 16, v20
	v_and_b32_e32 v75, 0xffff0000, v20
	v_lshlrev_b32_e32 v76, 16, v21
	v_and_b32_e32 v77, 0xffff0000, v21
	ds_write_b128 v65, v[74:77] offset:18432
	v_lshlrev_b32_e32 v74, 16, v22
	v_and_b32_e32 v75, 0xffff0000, v22
	v_lshlrev_b32_e32 v76, 16, v23
	v_and_b32_e32 v77, 0xffff0000, v23
	ds_write_b128 v65, v[74:77] offset:18448

.LBB0_709:
	s_ashr_i32 s11, s10, 31
	v_lshl_add_u64 v[32:33], s[10:11], 0, v[42:43]
	v_lshlrev_b64 v[32:33], 12, v[32:33]
	v_lshl_add_u64 v[32:33], v[56:57], 0, v[32:33]
	global_load_dwordx4 v[32:35], v[32:33], off
	s_and_saveexec_b64 s[28:29], s[6:7]
	s_cbranch_execz .LBB0_711
	v_lshl_add_u64 v[20:21], v[58:59], 0, s[10:11]
	v_lshlrev_b64 v[20:21], 11, v[20:21]
	v_lshl_add_u64 v[20:21], v[60:61], 0, v[20:21]
	global_load_dwordx4 v[20:23], v[20:21], off
